# unit heads of the six main GEMM phases: the generic 32-bit division by the row-group size (always 4 for 256 row tiles) replaced by shift and mask (-27 instructions incl. float reciprocal + readfirstla
# baseline (speedup 1.0000x reference)
;     __host__ __device__ __forceinline__ bool next(int i, Unit& u) const {
;         const long L = (long)i * G + c; if (L >= nwg) return false;
;         int wgid = (int)L; { const int q = nwg / NXCD, r = nwg % NXCD, xcd = wgid % NXCD, off = wgid / NXCD; wgid = (xcd < r ? xcd * (q + 1) : r * (q + 1) + (xcd - r) * q) + off; }
;         const int nig = WGM * nN, gid = wgid / nig, fm = gid * WGM, gsz = (nM - fm) < WGM ? (nM - fm) : WGM;
;         u.pm = fm + ((wgid % nig) % gsz); u.pn = (wgid % nig) / gsz; return true;
.LBB0_270:
	s_add_i32 s74, s74, 1
	s_mul_i32 s8, s74, s91
	s_mul_hi_u32 s9, s74, s3
	s_add_i32 s9, s9, s8
	s_mul_i32 s8, s74, s3
	s_add_u32 s10, s8, s92
	s_addc_u32 s11, s9, s7
	v_mov_b64_e32 v[0:1], 0x600
	v_cmp_lt_i64_e64 s[40:41], s[10:11], v[0:1]
	v_mov_b64_e32 v[0:1], 0x5ff
	v_cmp_gt_i64_e32 vcc, s[10:11], v[0:1]
	s_cbranch_vccnz .LBB0_272
	s_ashr_i32 s8, s10, 31
	s_lshr_b32 s8, s8, 29
	s_add_i32 s8, s10, s8
	s_ashr_i32 s9, s8, 3
	s_and_b32 s8, s8, -8
	s_sub_i32 s8, s10, s8
	s_cmp_lt_i32 s8, 0
	s_movk_i32 s2, 0xc1
	s_cselect_b32 s10, s2, 0xc0
	s_mul_i32 s8, s8, s10
	s_add_i32 s8, s8, s9
	s_mul_hi_i32 s9, s8, 0x2aaaaaab
	s_lshr_b32 s10, s9, 31
	s_ashr_i32 s9, s9, 2
	s_add_i32 s9, s9, s10
	s_lshl_b32 s10, s9, 2
	s_sub_i32 s11, 0x100, s10
	s_min_i32 s11, s11, 4
	s_mul_i32 s9, s9, 24
	s_sub_i32 s8, s8, s9
	s_lshr_b32 s94, s8, 2
	s_and_b32 s8, s8, 3
	s_add_i32 s76, s10, s8

;     __host__ __device__ __forceinline__ bool next(int i, Unit& u) const {
;         const long L = (long)i * G + c; if (L >= nwg) return false;
;         int wgid = (int)L; { const int q = nwg / NXCD, r = nwg % NXCD, xcd = wgid % NXCD, off = wgid / NXCD; wgid = (xcd < r ? xcd * (q + 1) : r * (q + 1) + (xcd - r) * q) + off; }
;         const int nig = WGM * nN, gid = wgid / nig, fm = gid * WGM, gsz = (nM - fm) < WGM ? (nM - fm) : WGM;
;         u.pm = fm + ((wgid % nig) % gsz); u.pn = (wgid % nig) / gsz; return true;
.LBB0_586:
	s_ashr_i32 s14, s16, 3
	s_add_i32 s14, s18, s14
	s_ashr_i32 s15, s14, 31
	s_lshr_b32 s15, s15, 28
	s_add_i32 s15, s14, s15
	s_ashr_i32 s16, s15, 4
	s_lshl_b32 s16, s16, 2
	s_sub_i32 s17, 0x100, s16
	s_min_i32 s17, s17, 4
	s_and_b32 s15, s15, -16
	s_sub_i32 s15, s14, s15
	s_lshr_b32 s14, s15, 2
	s_and_b32 s15, s15, 3
	s_add_i32 s16, s16, s15

;     __host__ __device__ __forceinline__ bool next(int i, Unit& u) const {
;         const long L = (long)i * G + c; if (L >= nwg) return false;
;         int wgid = (int)L; { const int q = nwg / NXCD, r = nwg % NXCD, xcd = wgid % NXCD, off = wgid / NXCD; wgid = (xcd < r ? xcd * (q + 1) : r * (q + 1) + (xcd - r) * q) + off; }
;         const int nig = WGM * nN, gid = wgid / nig, fm = gid * WGM, gsz = (nM - fm) < WGM ? (nM - fm) : WGM;
;         u.pm = fm + ((wgid % nig) % gsz); u.pn = (wgid % nig) / gsz; return true;
.LBB0_685:
	s_ashr_i32 s12, s16, 3
	s_add_i32 s12, s18, s12
	s_ashr_i32 s13, s12, 31
	s_lshr_b32 s13, s13, 28
	s_add_i32 s13, s12, s13
	s_ashr_i32 s16, s13, 4
	s_lshl_b32 s16, s16, 2
	s_sub_i32 s17, 0x100, s16
	s_min_i32 s17, s17, 4
	s_and_b32 s13, s13, -16
	s_sub_i32 s13, s12, s13
	s_lshr_b32 s12, s13, 2
	s_and_b32 s13, s13, 3
	s_add_i32 s16, s16, s13

;     __host__ __device__ __forceinline__ bool next(int i, Unit& u) const {
;         const long L = (long)i * G + c; if (L >= nwg) return false;
;         int wgid = (int)L; { const int q = nwg / NXCD, r = nwg % NXCD, xcd = wgid % NXCD, off = wgid / NXCD; wgid = (xcd < r ? xcd * (q + 1) : r * (q + 1) + (xcd - r) * q) + off; }
;         const int nig = WGM * nN, gid = wgid / nig, fm = gid * WGM, gsz = (nM - fm) < WGM ? (nM - fm) : WGM;
;         u.pm = fm + ((wgid % nig) % gsz); u.pn = (wgid % nig) / gsz; return true;
.LBB0_894:
	s_add_i32 s97, s97, 1
	s_mul_i32 s5, s97, s91
	s_mul_hi_u32 s11, s97, s3
	s_add_i32 s11, s11, s5
	s_mul_i32 s5, s97, s3
	v_readlane_b32 s18, v253, 20
	s_add_u32 s38, s5, s18
	s_addc_u32 s39, s11, s7
	v_mov_b64_e32 v[0:1], 0x1600
	v_cmp_lt_i64_e64 s[46:47], s[38:39], v[0:1]
	v_mov_b64_e32 v[0:1], 0x15ff
	v_cmp_gt_i64_e32 vcc, s[38:39], v[0:1]
	v_readlane_b32 s19, v253, 21
	s_cbranch_vccnz .LBB0_896
	s_ashr_i32 s4, s38, 31
	s_lshr_b32 s4, s4, 29
	s_add_i32 s4, s38, s4
	s_ashr_i32 s5, s4, 3
	s_and_b32 s4, s4, -8
	s_sub_i32 s4, s38, s4
	s_cmp_lt_i32 s4, 0
	s_movk_i32 s2, 0x2c1
	s_cselect_b32 s10, s2, 0x2c0
	s_mul_i32 s4, s4, s10
	s_add_i32 s4, s4, s5
	s_mul_hi_i32 s5, s4, 0x2e8ba2e9
	s_lshr_b32 s10, s5, 31
	s_ashr_i32 s5, s5, 4
	s_add_i32 s5, s5, s10
	s_lshl_b32 s10, s5, 2
	s_sub_i32 s11, 0x100, s10
	s_min_i32 s11, s11, 4
	s_mulk_i32 s5, 0x58
	s_sub_i32 s5, s4, s5
	s_lshr_b32 s4, s5, 2
	s_and_b32 s5, s5, 3
	s_add_i32 s10, s10, s5

;     __host__ __device__ __forceinline__ bool next(int i, Unit& u) const {
;         const long L = (long)i * G + c; if (L >= nwg) return false;
;         int wgid = (int)L; { const int q = nwg / NXCD, r = nwg % NXCD, xcd = wgid % NXCD, off = wgid / NXCD; wgid = (xcd < r ? xcd * (q + 1) : r * (q + 1) + (xcd - r) * q) + off; }
;         const int nig = WGM * nN, gid = wgid / nig, fm = gid * WGM, gsz = (nM - fm) < WGM ? (nM - fm) : WGM;
;         u.pm = fm + ((wgid % nig) % gsz); u.pn = (wgid % nig) / gsz; return true;
.LBB0_1025:
	s_ashr_i32 s2, s14, 3
	s_add_i32 s2, s22, s2
	s_ashr_i32 s12, s2, 31
	s_lshr_b32 s12, s12, 28
	s_add_i32 s12, s2, s12
	s_ashr_i32 s13, s12, 4
	s_lshl_b32 s13, s13, 2
	s_sub_i32 s14, 0x100, s13
	s_min_i32 s14, s14, 4
	s_and_b32 s12, s12, -16
	s_sub_i32 s2, s2, s12
	s_lshr_b32 s67, s2, 2
	s_and_b32 s2, s2, 3
	s_add_i32 s72, s13, s2
